# LN1-3: gain/bias loads of column groups 2-4 issued with group 1 (one round trip per row instead of four)
# baseline (speedup 1.0000x reference)
; __device__ __forceinline__ void ln_phase(int wv, h16* X, const float* g, const float* b, float* out32, int G, const float* part, float alpha, float beta) {
;     ...
; #pragma unroll
;         for (int e = 0; e < 32; ++e) s += v[e];
;         const float mean = wave_sum(s) * (1.f / DM); float s2 = 0.f;
; #pragma unroll
;         for (int e = 0; e < 32; ++e) { v[e] -= mean; s2 += v[e] * v[e]; }
;         const float rstd = 1.f / sqrtf(wave_sum(s2) * (1.f / DM) + LN_EPS);
; #pragma unroll
;         for (int j = 0; j < 4; ++j) { const int c0 = j * 512 + lane * 8;
;             const f32x4 g0 = *(const f32x4*)(g + c0), g1 = *(const f32x4*)(g + c0 + 4), b0 = *(const f32x4*)(b + c0), b1 = *(const f32x4*)(b + c0 + 4);
.LBB0_420:
	s_or_b64 exec, exec, s[8:9]
	v_add_f32_e32 v18, 0, v62
	v_add_f32_e32 v18, v63, v18
	v_add_f32_e32 v18, v60, v18
	v_add_f32_e32 v18, v61, v18
	v_add_f32_e32 v18, v58, v18
	v_add_f32_e32 v18, v59, v18
	v_add_f32_e32 v18, v28, v18
	v_add_f32_e32 v18, v29, v18
	v_add_f32_e32 v18, v30, v18
	v_add_f32_e32 v18, v31, v18
	v_add_f32_e32 v18, v64, v18
	v_add_f32_e32 v18, v65, v18
	v_add_f32_e32 v18, v24, v18
	v_add_f32_e32 v18, v25, v18
	v_add_f32_e32 v18, v66, v18
	v_add_f32_e32 v18, v67, v18
	v_add_f32_e32 v18, v26, v18
	v_add_f32_e32 v18, v27, v18
	v_add_f32_e32 v18, v68, v18
	v_add_f32_e32 v18, v69, v18
	v_add_f32_e32 v18, v20, v18
	v_add_f32_e32 v18, v21, v18
	v_add_f32_e32 v18, v70, v18
	v_add_f32_e32 v18, v71, v18
	v_add_f32_e32 v18, v22, v18
	v_add_f32_e32 v18, v23, v18
	v_add_f32_e32 v18, v72, v18
	v_add_f32_e32 v18, v73, v18
	v_add_f32_e32 v18, v16, v18
	v_add_f32_e32 v18, v17, v18
	v_add_f32_e32 v18, v74, v18
	v_add_f32_e32 v18, v75, v18
	ds_bpermute_b32 v19, v79, v18
	global_load_dwordx4 v[86:89], v[46:47], off offset:16
	global_load_dwordx4 v[90:93], v[46:47], off
	s_and_b64 s[6:7], exec, s[6:7]
	v_lshl_add_u64 v[38:39], v[38:39], 0, s[34:35]
	s_or_b64 s[16:17], s[6:7], s[16:17]
	s_waitcnt lgkmcnt(0)
	v_add_f32_e32 v18, v18, v19
	ds_bpermute_b32 v19, v80, v18
	v_mov_b32_e32 v76, v85
	s_waitcnt lgkmcnt(0)
	v_add_f32_e32 v18, v18, v19
	ds_bpermute_b32 v19, v81, v18
	s_waitcnt lgkmcnt(0)
	v_add_f32_e32 v18, v18, v19
	ds_bpermute_b32 v19, v82, v18
	s_waitcnt lgkmcnt(0)
	v_add_f32_e32 v18, v18, v19
	ds_bpermute_b32 v19, v83, v18
	s_waitcnt lgkmcnt(0)
	v_add_f32_e32 v18, v18, v19
	ds_bpermute_b32 v19, v84, v18
	s_waitcnt lgkmcnt(0)
	v_add_f32_e32 v18, v18, v19
	v_mul_f32_e32 v32, 0x3a000000, v18
	v_pk_add_f32 v[62:63], v[62:63], v[32:33] op_sel_hi:[1,0] neg_lo:[0,1] neg_hi:[0,1]
	v_pk_add_f32 v[60:61], v[60:61], v[32:33] op_sel_hi:[1,0] neg_lo:[0,1] neg_hi:[0,1]
	v_pk_mul_f32 v[124:125], v[62:63], v[62:63]
	v_pk_add_f32 v[94:95], v[30:31], v[32:33] op_sel_hi:[1,0] neg_lo:[0,1] neg_hi:[0,1]
	v_pk_add_f32 v[96:97], v[64:65], v[32:33] op_sel_hi:[1,0] neg_lo:[0,1] neg_hi:[0,1]
	v_pk_add_f32 v[98:99], v[24:25], v[32:33] op_sel_hi:[1,0] neg_lo:[0,1] neg_hi:[0,1]
	v_pk_add_f32 v[100:101], v[66:67], v[32:33] op_sel_hi:[1,0] neg_lo:[0,1] neg_hi:[0,1]
	v_pk_add_f32 v[102:103], v[26:27], v[32:33] op_sel_hi:[1,0] neg_lo:[0,1] neg_hi:[0,1]
	v_pk_add_f32 v[104:105], v[68:69], v[32:33] op_sel_hi:[1,0] neg_lo:[0,1] neg_hi:[0,1]
	v_pk_add_f32 v[106:107], v[20:21], v[32:33] op_sel_hi:[1,0] neg_lo:[0,1] neg_hi:[0,1]
	v_pk_add_f32 v[108:109], v[70:71], v[32:33] op_sel_hi:[1,0] neg_lo:[0,1] neg_hi:[0,1]
	v_pk_add_f32 v[64:65], v[22:23], v[32:33] op_sel_hi:[1,0] neg_lo:[0,1] neg_hi:[0,1]
	v_pk_add_f32 v[66:67], v[72:73], v[32:33] op_sel_hi:[1,0] neg_lo:[0,1] neg_hi:[0,1]
	v_pk_add_f32 v[68:69], v[16:17], v[32:33] op_sel_hi:[1,0] neg_lo:[0,1] neg_hi:[0,1]
	v_pk_add_f32 v[70:71], v[74:75], v[32:33] op_sel_hi:[1,0] neg_lo:[0,1] neg_hi:[0,1]
	v_pk_mul_f32 v[126:127], v[60:61], v[60:61]
	v_pk_add_f32 v[58:59], v[58:59], v[32:33] op_sel_hi:[1,0] neg_lo:[0,1] neg_hi:[0,1]
	v_pk_add_f32 v[28:29], v[28:29], v[32:33] op_sel_hi:[1,0] neg_lo:[0,1] neg_hi:[0,1]
	v_add_f32_e32 v32, v124, v125
	v_add_f32_e32 v32, v126, v32
	v_pk_mul_f32 v[128:129], v[58:59], v[58:59]
	v_add_f32_e32 v32, v127, v32
	v_add_f32_e32 v32, v128, v32
	v_pk_mul_f32 v[130:131], v[28:29], v[28:29]
	v_add_f32_e32 v32, v129, v32
	v_add_f32_e32 v32, v130, v32
	v_pk_mul_f32 v[24:25], v[94:95], v[94:95]
	v_add_f32_e32 v32, v131, v32
	v_add_f32_e32 v24, v24, v32
	v_pk_mul_f32 v[26:27], v[96:97], v[96:97]
	v_add_f32_e32 v24, v25, v24
	v_add_f32_e32 v24, v26, v24
	v_pk_mul_f32 v[30:31], v[98:99], v[98:99]
	v_add_f32_e32 v24, v27, v24
	v_add_f32_e32 v24, v30, v24
	v_pk_mul_f32 v[72:73], v[100:101], v[100:101]
	v_add_f32_e32 v24, v31, v24
	v_add_f32_e32 v24, v72, v24
	v_pk_mul_f32 v[74:75], v[102:103], v[102:103]
	v_add_f32_e32 v24, v73, v24
	v_add_f32_e32 v24, v74, v24
	v_pk_mul_f32 v[110:111], v[104:105], v[104:105]
	global_load_dwordx4 v[16:19], v[48:49], off offset:16
	global_load_dwordx4 v[20:23], v[48:49], off
	global_load_dwordx4 v[204:207], v[48:49], off offset:2048
	global_load_dwordx4 v[208:211], v[46:47], off offset:2048
	global_load_dwordx4 v[212:215], v[46:47], off offset:2064
	global_load_dwordx4 v[216:219], v[48:49], off offset:2064
	global_load_dwordx4 v[220:223], v[52:53], off
	global_load_dwordx4 v[224:227], v[50:51], off
	global_load_dwordx4 v[228:231], v[50:51], off offset:16
	global_load_dwordx4 v[232:235], v[52:53], off offset:16
	global_load_dwordx4 v[240:243], v[56:57], off
	global_load_dwordx4 v[244:247], v[54:55], off
	global_load_dwordx4 v[248:251], v[54:55], off offset:16
	global_load_dwordx4 v[252:255], v[56:57], off offset:16
	v_add_f32_e32 v24, v75, v24
	v_add_f32_e32 v24, v110, v24
	v_pk_mul_f32 v[112:113], v[106:107], v[106:107]
	v_add_f32_e32 v24, v111, v24
	v_add_f32_e32 v24, v112, v24
	v_pk_mul_f32 v[114:115], v[108:109], v[108:109]
	v_add_f32_e32 v24, v113, v24
	v_add_f32_e32 v24, v114, v24
	v_pk_mul_f32 v[116:117], v[64:65], v[64:65]
	v_add_f32_e32 v24, v115, v24
	v_add_f32_e32 v24, v116, v24
	v_pk_mul_f32 v[118:119], v[66:67], v[66:67]
	v_add_f32_e32 v24, v117, v24
	v_add_f32_e32 v24, v118, v24
	v_pk_mul_f32 v[120:121], v[68:69], v[68:69]
	v_add_f32_e32 v24, v119, v24
	v_add_f32_e32 v24, v120, v24
	v_pk_mul_f32 v[122:123], v[70:71], v[70:71]
	v_add_f32_e32 v24, v121, v24
	v_add_f32_e32 v24, v122, v24
	v_add_f32_e32 v24, v123, v24
	ds_bpermute_b32 v25, v79, v24
	s_waitcnt lgkmcnt(0)
; __device__ __forceinline__ void ln_phase(int wv, h16* X, const float* g, const float* b, float* out32, int G, const float* part, float alpha, float beta) {
;     ...
;         const float rstd = 1.f / sqrtf(wave_sum(s2) * (1.f / DM) + LN_EPS);
; #pragma unroll
;         for (int j = 0; j < 4; ++j) { const int c0 = j * 512 + lane * 8;
;             const f32x4 g0 = *(const f32x4*)(g + c0), g1 = *(const f32x4*)(g + c0 + 4), b0 = *(const f32x4*)(b + c0), b1 = *(const f32x4*)(b + c0 + 4);
;             f32x4 o0, o1;
; #pragma unroll
;             for (int e = 0; e < 4; ++e) { o0[e] = v[j * 8 + e] * rstd * g0[e] + b0[e]; o1[e] = v[j * 8 + 4 + e] * rstd * g1[e] + b1[e]; }
;             if (out32) { *(f32x4*)(out32 + (size_t)row * DM + c0) = o0; *(f32x4*)(out32 + (size_t)row * DM + c0 + 4) = o1; }
;             else *(u32x4*)(xr + c0) = pg8::pack8(o0, o1); }
	v_add_f32_e32 v24, v24, v25
	ds_bpermute_b32 v25, v80, v24
	s_waitcnt lgkmcnt(0)
	v_add_f32_e32 v24, v24, v25
	ds_bpermute_b32 v25, v81, v24
	s_waitcnt lgkmcnt(0)
	v_add_f32_e32 v24, v24, v25
	ds_bpermute_b32 v25, v82, v24
	s_waitcnt lgkmcnt(0)
	v_add_f32_e32 v24, v24, v25
	ds_bpermute_b32 v25, v83, v24
	s_waitcnt lgkmcnt(0)
	v_add_f32_e32 v24, v24, v25
	ds_bpermute_b32 v25, v84, v24
	s_waitcnt lgkmcnt(0)
	v_add_f32_e32 v24, v24, v25
	v_fmamk_f32 v24, v24, 0x3a000000, v77
	v_mul_f32_e32 v25, 0x4f800000, v24
	v_cmp_gt_f32_e32 vcc, s37, v24
	s_nop 1
	v_cndmask_b32_e32 v24, v24, v25, vcc
	v_sqrt_f32_e32 v25, v24
	s_nop 0
	v_add_u32_e32 v26, -1, v25
	v_add_u32_e32 v27, 1, v25
	v_fma_f32 v30, -v26, v25, v24
	v_fma_f32 v31, -v27, v25, v24
	v_cmp_ge_f32_e64 s[8:9], 0, v30
	s_nop 1
	v_cndmask_b32_e64 v25, v25, v26, s[8:9]
	v_cmp_lt_f32_e64 s[8:9], 0, v31
	s_nop 1
	v_cndmask_b32_e64 v25, v25, v27, s[8:9]
	v_mul_f32_e32 v26, 0x37800000, v25
	v_cndmask_b32_e32 v25, v25, v26, vcc
	v_cmp_class_f32_e32 vcc, v24, v78
	s_nop 1
	v_cndmask_b32_e32 v26, v25, v24, vcc
	v_div_scale_f32 v27, s[8:9], v26, v26, 1.0
	v_rcp_f32_e32 v30, v27
	v_div_scale_f32 v31, vcc, 1.0, v26, 1.0
	v_lshl_add_u64 v[24:25], v[36:37], 0, v[34:35]
	v_fma_f32 v32, -v27, v30, 1.0
	v_fmac_f32_e32 v30, v32, v30
	v_mul_f32_e32 v32, v31, v30
	v_fma_f32 v72, -v27, v32, v31
	v_fmac_f32_e32 v32, v72, v30
	v_fma_f32 v27, -v27, v32, v31
	v_div_fmas_f32 v27, v27, v30, v32
	v_div_fixup_f32 v32, v27, v26, 1.0
	v_pk_mul_f32 v[26:27], v[62:63], v[32:33] op_sel_hi:[1,0]
	v_pk_mul_f32 v[30:31], v[58:59], v[32:33] op_sel_hi:[1,0]
	v_pk_mul_f32 v[58:59], v[60:61], v[32:33] op_sel_hi:[1,0]
	v_pk_mul_f32 v[28:29], v[28:29], v[32:33] op_sel_hi:[1,0]
	s_waitcnt vmcnt(0)
	v_pk_fma_f32 v[20:21], v[90:91], v[26:27], v[20:21]
	v_pk_fma_f32 v[26:27], v[86:87], v[30:31], v[16:17]
	v_pk_fma_f32 v[22:23], v[92:93], v[58:59], v[22:23]
	v_pk_fma_f32 v[28:29], v[88:89], v[28:29], v[18:19]
	v_add_co_u32_e32 v62, vcc, s3, v24
	v_cvt_pk_f16_f32 v16, v20, v21
	v_cvt_pk_f16_f32 v17, v22, v23
	v_cvt_pk_f16_f32 v18, v26, v27
	v_cvt_pk_f16_f32 v19, v28, v29
	v_addc_co_u32_e32 v63, vcc, 0, v25, vcc
	global_store_dwordx4 v[62:63], v[16:19], off
	s_nop 0
	v_pk_mul_f32 v[58:59], v[94:95], v[32:33] op_sel_hi:[1,0]
	v_pk_mul_f32 v[60:61], v[96:97], v[32:33] op_sel_hi:[1,0]
	v_pk_mul_f32 v[72:73], v[98:99], v[32:33] op_sel_hi:[1,0]
	v_pk_mul_f32 v[74:75], v[100:101], v[32:33] op_sel_hi:[1,0]
	v_pk_mul_f32 v[64:65], v[64:65], v[32:33] op_sel_hi:[1,0]
	v_pk_mul_f32 v[66:67], v[66:67], v[32:33] op_sel_hi:[1,0]
	v_pk_mul_f32 v[68:69], v[68:69], v[32:33] op_sel_hi:[1,0]
	v_pk_mul_f32 v[70:71], v[70:71], v[32:33] op_sel_hi:[1,0]
	v_lshl_add_u64 v[36:37], v[36:37], 0, s[34:35]
	v_pk_fma_f32 v[16:17], v[208:209], v[58:59], v[204:205]
	v_pk_fma_f32 v[18:19], v[210:211], v[60:61], v[206:207]
	v_pk_fma_f32 v[20:21], v[212:213], v[72:73], v[216:217]
	v_pk_fma_f32 v[22:23], v[214:215], v[74:75], v[218:219]
	v_cvt_pk_f16_f32 v16, v16, v17
	v_cvt_pk_f16_f32 v17, v18, v19
	v_cvt_pk_f16_f32 v18, v20, v21
	v_cvt_pk_f16_f32 v19, v22, v23
	global_store_dwordx4 v[62:63], v[16:19], off offset:1024
	s_nop 0
	v_pk_mul_f32 v[58:59], v[102:103], v[32:33] op_sel_hi:[1,0]
	v_pk_mul_f32 v[60:61], v[104:105], v[32:33] op_sel_hi:[1,0]
	v_pk_mul_f32 v[72:73], v[106:107], v[32:33] op_sel_hi:[1,0]
	v_pk_mul_f32 v[74:75], v[108:109], v[32:33] op_sel_hi:[1,0]
	v_pk_fma_f32 v[16:17], v[224:225], v[58:59], v[220:221]
	v_pk_fma_f32 v[18:19], v[226:227], v[60:61], v[222:223]
	v_pk_fma_f32 v[20:21], v[228:229], v[72:73], v[232:233]
	v_pk_fma_f32 v[22:23], v[230:231], v[74:75], v[234:235]
	v_cvt_pk_f16_f32 v16, v16, v17
	v_cvt_pk_f16_f32 v17, v18, v19
	v_cvt_pk_f16_f32 v18, v20, v21
	v_cvt_pk_f16_f32 v19, v22, v23
	global_store_dwordx4 v[62:63], v[16:19], off offset:2048
	v_mov_b64_e32 v[30:31], v[2:3]
	v_mov_b64_e32 v[26:27], v[6:7]
	v_mov_b64_e32 v[22:23], v[10:11]
	v_mov_b64_e32 v[18:19], v[14:15]
	v_mov_b64_e32 v[28:29], v[0:1]
	v_mov_b64_e32 v[24:25], v[4:5]
	v_mov_b64_e32 v[20:21], v[8:9]
	v_mov_b64_e32 v[16:17], v[12:13]
	v_pk_fma_f32 v[58:59], v[244:245], v[64:65], v[240:241]
	v_pk_fma_f32 v[60:61], v[246:247], v[66:67], v[242:243]
	v_pk_fma_f32 v[64:65], v[248:249], v[68:69], v[252:253]
	v_pk_fma_f32 v[66:67], v[250:251], v[70:71], v[254:255]
	v_cvt_pk_f16_f32 v58, v58, v59
	v_cvt_pk_f16_f32 v59, v60, v61
	v_cvt_pk_f16_f32 v60, v64, v65
	v_cvt_pk_f16_f32 v61, v66, v67
	global_store_dwordx4 v[62:63], v[58:61], off offset:3072
	s_andn2_b64 exec, exec, s[16:17]
	s_cbranch_execz .LBB0_425

; __device__ __forceinline__ void ln_phase(int wv, h16* X, const float* g, const float* b, float* out32, int G, const float* part, float alpha, float beta) {
;     ...
; #pragma unroll
;         for (int e = 0; e < 32; ++e) s += v[e];
;         const float mean = wave_sum(s) * (1.f / DM); float s2 = 0.f;
; #pragma unroll
;         for (int e = 0; e < 32; ++e) { v[e] -= mean; s2 += v[e] * v[e]; }
;         const float rstd = 1.f / sqrtf(wave_sum(s2) * (1.f / DM) + LN_EPS);
; #pragma unroll
;         for (int j = 0; j < 4; ++j) { const int c0 = j * 512 + lane * 8;
;             const f32x4 g0 = *(const f32x4*)(g + c0), g1 = *(const f32x4*)(g + c0 + 4), b0 = *(const f32x4*)(b + c0), b1 = *(const f32x4*)(b + c0 + 4);
.LBB0_2266:
	s_or_b64 exec, exec, s[8:9]
	v_add_f32_e32 v18, 0, v66
	v_add_f32_e32 v18, v67, v18
	v_add_f32_e32 v18, v64, v18
	v_add_f32_e32 v18, v65, v18
	v_add_f32_e32 v18, v62, v18
	v_add_f32_e32 v18, v63, v18
	v_add_f32_e32 v18, v28, v18
	v_add_f32_e32 v18, v29, v18
	v_add_f32_e32 v18, v30, v18
	v_add_f32_e32 v18, v31, v18
	v_add_f32_e32 v18, v68, v18
	v_add_f32_e32 v18, v69, v18
	v_add_f32_e32 v18, v24, v18
	v_add_f32_e32 v18, v25, v18
	v_add_f32_e32 v18, v70, v18
	v_add_f32_e32 v18, v71, v18
	v_add_f32_e32 v18, v26, v18
	v_add_f32_e32 v18, v27, v18
	v_add_f32_e32 v18, v72, v18
	v_add_f32_e32 v18, v73, v18
	v_add_f32_e32 v18, v20, v18
	v_add_f32_e32 v18, v21, v18
	v_add_f32_e32 v18, v74, v18
	v_add_f32_e32 v18, v75, v18
	v_add_f32_e32 v18, v22, v18
	v_add_f32_e32 v18, v23, v18
	v_add_f32_e32 v18, v76, v18
	v_add_f32_e32 v18, v77, v18
	v_add_f32_e32 v18, v16, v18
	v_add_f32_e32 v18, v17, v18
	v_add_f32_e32 v18, v78, v18
	v_add_f32_e32 v18, v79, v18
	ds_bpermute_b32 v19, v171, v18
	global_load_dwordx4 v[84:87], v[52:53], off offset:16
	global_load_dwordx4 v[88:91], v[52:53], off
	s_and_b64 s[6:7], exec, s[6:7]
	v_lshl_add_u64 v[38:39], v[38:39], 0, s[10:11]
	s_or_b64 s[14:15], s[6:7], s[14:15]
	s_waitcnt lgkmcnt(0)
	v_add_f32_e32 v18, v18, v19
	ds_bpermute_b32 v19, v172, v18
	v_mov_b32_e32 v80, v83
	s_waitcnt lgkmcnt(0)
	v_add_f32_e32 v18, v18, v19
	ds_bpermute_b32 v19, v173, v18
	s_waitcnt lgkmcnt(0)
	v_add_f32_e32 v18, v18, v19
	ds_bpermute_b32 v19, v174, v18
	s_waitcnt lgkmcnt(0)
	v_add_f32_e32 v18, v18, v19
	ds_bpermute_b32 v19, v175, v18
	s_waitcnt lgkmcnt(0)
	v_add_f32_e32 v18, v18, v19
	ds_bpermute_b32 v19, v176, v18
	s_waitcnt lgkmcnt(0)
	v_add_f32_e32 v18, v18, v19
	v_mul_f32_e32 v32, 0x3a000000, v18
	v_pk_add_f32 v[66:67], v[66:67], v[32:33] op_sel_hi:[1,0] neg_lo:[0,1] neg_hi:[0,1]
	v_pk_add_f32 v[64:65], v[64:65], v[32:33] op_sel_hi:[1,0] neg_lo:[0,1] neg_hi:[0,1]
	v_pk_mul_f32 v[122:123], v[66:67], v[66:67]
	v_pk_add_f32 v[92:93], v[30:31], v[32:33] op_sel_hi:[1,0] neg_lo:[0,1] neg_hi:[0,1]
	v_pk_add_f32 v[94:95], v[68:69], v[32:33] op_sel_hi:[1,0] neg_lo:[0,1] neg_hi:[0,1]
	v_pk_add_f32 v[96:97], v[24:25], v[32:33] op_sel_hi:[1,0] neg_lo:[0,1] neg_hi:[0,1]
	v_pk_add_f32 v[98:99], v[70:71], v[32:33] op_sel_hi:[1,0] neg_lo:[0,1] neg_hi:[0,1]
	v_pk_add_f32 v[100:101], v[26:27], v[32:33] op_sel_hi:[1,0] neg_lo:[0,1] neg_hi:[0,1]
	v_pk_add_f32 v[102:103], v[72:73], v[32:33] op_sel_hi:[1,0] neg_lo:[0,1] neg_hi:[0,1]
	v_pk_add_f32 v[104:105], v[20:21], v[32:33] op_sel_hi:[1,0] neg_lo:[0,1] neg_hi:[0,1]
	v_pk_add_f32 v[106:107], v[74:75], v[32:33] op_sel_hi:[1,0] neg_lo:[0,1] neg_hi:[0,1]
	v_pk_add_f32 v[68:69], v[22:23], v[32:33] op_sel_hi:[1,0] neg_lo:[0,1] neg_hi:[0,1]
	v_pk_add_f32 v[70:71], v[76:77], v[32:33] op_sel_hi:[1,0] neg_lo:[0,1] neg_hi:[0,1]
	v_pk_add_f32 v[72:73], v[16:17], v[32:33] op_sel_hi:[1,0] neg_lo:[0,1] neg_hi:[0,1]
	v_pk_add_f32 v[74:75], v[78:79], v[32:33] op_sel_hi:[1,0] neg_lo:[0,1] neg_hi:[0,1]
	v_pk_mul_f32 v[124:125], v[64:65], v[64:65]
	v_pk_add_f32 v[62:63], v[62:63], v[32:33] op_sel_hi:[1,0] neg_lo:[0,1] neg_hi:[0,1]
	v_pk_add_f32 v[28:29], v[28:29], v[32:33] op_sel_hi:[1,0] neg_lo:[0,1] neg_hi:[0,1]
	v_add_f32_e32 v32, v122, v123
	v_add_f32_e32 v32, v124, v32
	v_pk_mul_f32 v[126:127], v[62:63], v[62:63]
	v_add_f32_e32 v32, v125, v32
	v_add_f32_e32 v32, v126, v32
	v_pk_mul_f32 v[128:129], v[28:29], v[28:29]
	v_add_f32_e32 v32, v127, v32
	v_add_f32_e32 v32, v128, v32
	v_pk_mul_f32 v[24:25], v[92:93], v[92:93]
	v_add_f32_e32 v32, v129, v32
	v_add_f32_e32 v24, v24, v32
	v_pk_mul_f32 v[26:27], v[94:95], v[94:95]
	v_add_f32_e32 v24, v25, v24
	v_add_f32_e32 v24, v26, v24
	v_pk_mul_f32 v[30:31], v[96:97], v[96:97]
	v_add_f32_e32 v24, v27, v24
	v_add_f32_e32 v24, v30, v24
	v_pk_mul_f32 v[76:77], v[98:99], v[98:99]
	v_add_f32_e32 v24, v31, v24
	v_add_f32_e32 v24, v76, v24
	v_pk_mul_f32 v[78:79], v[100:101], v[100:101]
	v_add_f32_e32 v24, v77, v24
	v_add_f32_e32 v24, v78, v24
	v_pk_mul_f32 v[108:109], v[102:103], v[102:103]
	global_load_dwordx4 v[16:19], v[46:47], off offset:16
	global_load_dwordx4 v[20:23], v[46:47], off
	global_load_dwordx4 v[204:207], v[48:49], off
	global_load_dwordx4 v[208:211], v[54:55], off
	global_load_dwordx4 v[212:215], v[54:55], off offset:16
	global_load_dwordx4 v[216:219], v[48:49], off offset:16
	global_load_dwordx4 v[220:223], v[50:51], off
	global_load_dwordx4 v[224:227], v[56:57], off
	global_load_dwordx4 v[228:231], v[56:57], off offset:16
	global_load_dwordx4 v[232:235], v[50:51], off offset:16
	global_load_dwordx4 v[240:243], v[60:61], off
	global_load_dwordx4 v[244:247], v[58:59], off
	global_load_dwordx4 v[248:251], v[58:59], off offset:16
	global_load_dwordx4 v[252:255], v[60:61], off offset:16
	v_add_f32_e32 v24, v79, v24
	v_add_f32_e32 v24, v108, v24
	v_pk_mul_f32 v[110:111], v[104:105], v[104:105]
	v_add_f32_e32 v24, v109, v24
	v_add_f32_e32 v24, v110, v24
	v_pk_mul_f32 v[112:113], v[106:107], v[106:107]
	v_add_f32_e32 v24, v111, v24
	v_add_f32_e32 v24, v112, v24
	v_pk_mul_f32 v[114:115], v[68:69], v[68:69]
	v_add_f32_e32 v24, v113, v24
	v_add_f32_e32 v24, v114, v24
	v_pk_mul_f32 v[116:117], v[70:71], v[70:71]
	v_add_f32_e32 v24, v115, v24
	v_add_f32_e32 v24, v116, v24
	v_pk_mul_f32 v[118:119], v[72:73], v[72:73]
	v_add_f32_e32 v24, v117, v24
	v_add_f32_e32 v24, v118, v24
	v_pk_mul_f32 v[120:121], v[74:75], v[74:75]
	v_add_f32_e32 v24, v119, v24
	v_add_f32_e32 v24, v120, v24
	v_add_f32_e32 v24, v121, v24
	ds_bpermute_b32 v25, v171, v24
	s_waitcnt lgkmcnt(0)
; __device__ __forceinline__ void ln_phase(int wv, h16* X, const float* g, const float* b, float* out32, int G, const float* part, float alpha, float beta) {
;     ...
;         const float rstd = 1.f / sqrtf(wave_sum(s2) * (1.f / DM) + LN_EPS);
; #pragma unroll
;         for (int j = 0; j < 4; ++j) { const int c0 = j * 512 + lane * 8;
;             const f32x4 g0 = *(const f32x4*)(g + c0), g1 = *(const f32x4*)(g + c0 + 4), b0 = *(const f32x4*)(b + c0), b1 = *(const f32x4*)(b + c0 + 4);
;             f32x4 o0, o1;
; #pragma unroll
;             for (int e = 0; e < 4; ++e) { o0[e] = v[j * 8 + e] * rstd * g0[e] + b0[e]; o1[e] = v[j * 8 + 4 + e] * rstd * g1[e] + b1[e]; }
;             if (out32) { *(f32x4*)(out32 + (size_t)row * DM + c0) = o0; *(f32x4*)(out32 + (size_t)row * DM + c0 + 4) = o1; }
;             else *(u32x4*)(xr + c0) = pg8::pack8(o0, o1); }
	v_add_f32_e32 v24, v24, v25
	ds_bpermute_b32 v25, v172, v24
	s_waitcnt lgkmcnt(0)
	v_add_f32_e32 v24, v24, v25
	ds_bpermute_b32 v25, v173, v24
	s_waitcnt lgkmcnt(0)
	v_add_f32_e32 v24, v24, v25
	ds_bpermute_b32 v25, v174, v24
	s_waitcnt lgkmcnt(0)
	v_add_f32_e32 v24, v24, v25
	ds_bpermute_b32 v25, v175, v24
	s_waitcnt lgkmcnt(0)
	v_add_f32_e32 v24, v24, v25
	ds_bpermute_b32 v25, v176, v24
	s_waitcnt lgkmcnt(0)
	v_add_f32_e32 v24, v24, v25
	v_fmamk_f32 v24, v24, 0x3a000000, v81
	v_mul_f32_e32 v25, 0x4f800000, v24
	v_cmp_gt_f32_e32 vcc, s31, v24
	s_nop 1
	v_cndmask_b32_e32 v24, v24, v25, vcc
	v_sqrt_f32_e32 v25, v24
	s_nop 0
	v_add_u32_e32 v26, -1, v25
	v_add_u32_e32 v27, 1, v25
	v_fma_f32 v30, -v26, v25, v24
	v_fma_f32 v31, -v27, v25, v24
	v_cmp_ge_f32_e64 s[8:9], 0, v30
	s_nop 1
	v_cndmask_b32_e64 v25, v25, v26, s[8:9]
	v_cmp_lt_f32_e64 s[8:9], 0, v31
	s_nop 1
	v_cndmask_b32_e64 v25, v25, v27, s[8:9]
	v_mul_f32_e32 v26, 0x37800000, v25
	v_cndmask_b32_e32 v25, v25, v26, vcc
	v_cmp_class_f32_e32 vcc, v24, v82
	s_nop 1
	v_cndmask_b32_e32 v26, v25, v24, vcc
	v_div_scale_f32 v27, s[8:9], v26, v26, 1.0
	v_rcp_f32_e32 v30, v27
	v_div_scale_f32 v31, vcc, 1.0, v26, 1.0
	v_lshl_add_u64 v[24:25], v[36:37], 0, v[34:35]
	v_fma_f32 v32, -v27, v30, 1.0
	v_fmac_f32_e32 v30, v32, v30
	v_mul_f32_e32 v32, v31, v30
	v_fma_f32 v76, -v27, v32, v31
	v_fmac_f32_e32 v32, v76, v30
	v_fma_f32 v27, -v27, v32, v31
	v_div_fmas_f32 v27, v27, v30, v32
	v_div_fixup_f32 v32, v27, v26, 1.0
	v_pk_mul_f32 v[26:27], v[66:67], v[32:33] op_sel_hi:[1,0]
	v_pk_mul_f32 v[30:31], v[62:63], v[32:33] op_sel_hi:[1,0]
	v_pk_mul_f32 v[62:63], v[64:65], v[32:33] op_sel_hi:[1,0]
	v_pk_mul_f32 v[28:29], v[28:29], v[32:33] op_sel_hi:[1,0]
	s_waitcnt vmcnt(0)
	v_pk_fma_f32 v[20:21], v[88:89], v[26:27], v[20:21]
	v_pk_fma_f32 v[26:27], v[84:85], v[30:31], v[16:17]
	v_pk_fma_f32 v[22:23], v[90:91], v[62:63], v[22:23]
	v_pk_fma_f32 v[28:29], v[86:87], v[28:29], v[18:19]
	v_add_co_u32_e32 v66, vcc, s3, v24
	v_cvt_pk_f16_f32 v16, v20, v21
	v_cvt_pk_f16_f32 v17, v22, v23
	v_cvt_pk_f16_f32 v18, v26, v27
	v_cvt_pk_f16_f32 v19, v28, v29
	v_addc_co_u32_e32 v67, vcc, 0, v25, vcc
	global_store_dwordx4 v[66:67], v[16:19], off
	s_nop 0
	v_pk_mul_f32 v[62:63], v[92:93], v[32:33] op_sel_hi:[1,0]
	v_pk_mul_f32 v[64:65], v[94:95], v[32:33] op_sel_hi:[1,0]
	v_pk_mul_f32 v[76:77], v[96:97], v[32:33] op_sel_hi:[1,0]
	v_pk_mul_f32 v[78:79], v[98:99], v[32:33] op_sel_hi:[1,0]
	v_pk_mul_f32 v[68:69], v[68:69], v[32:33] op_sel_hi:[1,0]
	v_pk_mul_f32 v[70:71], v[70:71], v[32:33] op_sel_hi:[1,0]
	v_pk_mul_f32 v[72:73], v[72:73], v[32:33] op_sel_hi:[1,0]
	v_pk_mul_f32 v[74:75], v[74:75], v[32:33] op_sel_hi:[1,0]
	v_lshl_add_u64 v[36:37], v[36:37], 0, s[10:11]
	v_pk_fma_f32 v[16:17], v[208:209], v[62:63], v[204:205]
	v_pk_fma_f32 v[18:19], v[210:211], v[64:65], v[206:207]
	v_pk_fma_f32 v[20:21], v[212:213], v[76:77], v[216:217]
	v_pk_fma_f32 v[22:23], v[214:215], v[78:79], v[218:219]
	v_cvt_pk_f16_f32 v16, v16, v17
	v_cvt_pk_f16_f32 v17, v18, v19
	v_cvt_pk_f16_f32 v18, v20, v21
	v_cvt_pk_f16_f32 v19, v22, v23
	global_store_dwordx4 v[66:67], v[16:19], off offset:1024
	s_nop 0
	v_pk_mul_f32 v[62:63], v[100:101], v[32:33] op_sel_hi:[1,0]
	v_pk_mul_f32 v[64:65], v[102:103], v[32:33] op_sel_hi:[1,0]
	v_pk_mul_f32 v[76:77], v[104:105], v[32:33] op_sel_hi:[1,0]
	v_pk_mul_f32 v[78:79], v[106:107], v[32:33] op_sel_hi:[1,0]
	v_pk_fma_f32 v[16:17], v[224:225], v[62:63], v[220:221]
	v_pk_fma_f32 v[18:19], v[226:227], v[64:65], v[222:223]
	v_pk_fma_f32 v[20:21], v[228:229], v[76:77], v[232:233]
	v_pk_fma_f32 v[22:23], v[230:231], v[78:79], v[234:235]
	v_cvt_pk_f16_f32 v16, v16, v17
	v_cvt_pk_f16_f32 v17, v18, v19
	v_cvt_pk_f16_f32 v18, v20, v21
	v_cvt_pk_f16_f32 v19, v22, v23
	global_store_dwordx4 v[66:67], v[16:19], off offset:2048
	v_mov_b64_e32 v[30:31], v[2:3]
	v_mov_b64_e32 v[26:27], v[6:7]
	v_mov_b64_e32 v[22:23], v[10:11]
	v_mov_b64_e32 v[18:19], v[14:15]
	v_mov_b64_e32 v[28:29], v[0:1]
	v_mov_b64_e32 v[24:25], v[4:5]
	v_mov_b64_e32 v[20:21], v[8:9]
	v_mov_b64_e32 v[16:17], v[12:13]
	v_pk_fma_f32 v[62:63], v[244:245], v[68:69], v[240:241]
	v_pk_fma_f32 v[64:65], v[246:247], v[70:71], v[242:243]
	v_pk_fma_f32 v[68:69], v[248:249], v[72:73], v[252:253]
	v_pk_fma_f32 v[70:71], v[250:251], v[74:75], v[254:255]
	v_cvt_pk_f16_f32 v62, v62, v63
	v_cvt_pk_f16_f32 v63, v64, v65
	v_cvt_pk_f16_f32 v64, v68, v69
	v_cvt_pk_f16_f32 v65, v70, v71
	global_store_dwordx4 v[66:67], v[62:65], off offset:3072
	s_andn2_b64 exec, exec, s[14:15]
	s_cbranch_execz .LBB0_2271

; __device__ __forceinline__ void ln_phase(int wv, h16* X, const float* g, const float* b, float* out32, int G, const float* part, float alpha, float beta) {
;     ...
;         for (int j = 0; j < 4; ++j) { const h16x8 h = __builtin_bit_cast(h16x8, cu[j]);
; #pragma unroll
;             for (int e = 0; e < 8; ++e) v[j * 8 + e] = (float)h[e]; }
;         if (part && row >= NP) {
; #pragma unroll
;             for (int j = 0; j < 4; ++j) { f32x4 a0 = {0.f, 0.f, 0.f, 0.f}, a1 = {0.f, 0.f, 0.f, 0.f};
; #pragma unroll
;                 for (int ks = 0; ks < 4; ++ks) { const float* p = part + ((size_t)ks * NS + (row - NP)) * DM + j * 512 + lane * 8; a0 += *(const f32x4*)p; a1 += *(const f32x4*)(p + 4); }
; #pragma unroll
;                 for (int e = 0; e < 4; ++e) { v[j * 8 + e] = alpha * v[j * 8 + e] + beta * a0[e]; v[j * 8 + 4 + e] = alpha * v[j * 8 + 4 + e] + beta * a1[e]; } } }
; #pragma unroll
;         for (int e = 0; e < 32; ++e) s += v[e];
;         const float mean = wave_sum(s) * (1.f / DM); float s2 = 0.f;
; #pragma unroll
;         for (int e = 0; e < 32; ++e) { v[e] -= mean; s2 += v[e] * v[e]; }
;         const float rstd = 1.f / sqrtf(wave_sum(s2) * (1.f / DM) + LN_EPS);
; #pragma unroll
;         for (int j = 0; j < 4; ++j) { const int c0 = j * 512 + lane * 8;
;             const f32x4 g0 = *(const f32x4*)(g + c0), g1 = *(const f32x4*)(g + c0 + 4), b0 = *(const f32x4*)(b + c0), b1 = *(const f32x4*)(b + c0 + 4);
.LBB0_2528:
	s_or_b64 exec, exec, s[8:9]
	v_cvt_f32_f16_e32 v58, v28
	v_cvt_f32_f16_sdwa v59, v28 dst_sel:DWORD dst_unused:UNUSED_PAD src0_sel:WORD_1
	v_cvt_f32_f16_e32 v60, v29
	v_cvt_f32_f16_sdwa v61, v29 dst_sel:DWORD dst_unused:UNUSED_PAD src0_sel:WORD_1
	v_add_f32_e32 v28, 0, v58
	v_cvt_f32_f16_e32 v62, v30
	v_add_f32_e32 v28, v28, v59
	v_cvt_f32_f16_sdwa v63, v30 dst_sel:DWORD dst_unused:UNUSED_PAD src0_sel:WORD_1
	v_add_f32_e32 v28, v28, v60
	v_cvt_f32_f16_e32 v64, v31
	v_add_f32_e32 v28, v28, v61
	v_cvt_f32_f16_sdwa v65, v31 dst_sel:DWORD dst_unused:UNUSED_PAD src0_sel:WORD_1
	v_add_f32_e32 v28, v28, v62
	v_cvt_f32_f16_e32 v66, v24
	v_add_f32_e32 v28, v28, v63
	v_cvt_f32_f16_sdwa v67, v24 dst_sel:DWORD dst_unused:UNUSED_PAD src0_sel:WORD_1
	v_add_f32_e32 v28, v28, v64
	v_cvt_f32_f16_e32 v70, v25
	v_add_f32_e32 v28, v28, v65
	v_cvt_f32_f16_sdwa v71, v25 dst_sel:DWORD dst_unused:UNUSED_PAD src0_sel:WORD_1
	v_cvt_f32_f16_sdwa v69, v19 dst_sel:DWORD dst_unused:UNUSED_PAD src0_sel:WORD_1
	v_cvt_f32_f16_e32 v68, v19
	v_add_f32_e32 v19, v28, v66
	v_cvt_f32_f16_e32 v72, v26
	v_add_f32_e32 v19, v19, v67
	v_cvt_f32_f16_sdwa v73, v26 dst_sel:DWORD dst_unused:UNUSED_PAD src0_sel:WORD_1
	v_add_f32_e32 v19, v19, v70
	v_cvt_f32_f16_e32 v74, v27
	v_add_f32_e32 v19, v19, v71
	v_cvt_f32_f16_sdwa v75, v27 dst_sel:DWORD dst_unused:UNUSED_PAD src0_sel:WORD_1
	v_add_f32_e32 v19, v19, v72
	v_cvt_f32_f16_e32 v76, v20
	v_add_f32_e32 v19, v19, v73
	v_cvt_f32_f16_sdwa v77, v20 dst_sel:DWORD dst_unused:UNUSED_PAD src0_sel:WORD_1
	v_add_f32_e32 v19, v19, v74
	v_cvt_f32_f16_e32 v78, v21
	v_add_f32_e32 v19, v19, v75
	v_cvt_f32_f16_sdwa v79, v21 dst_sel:DWORD dst_unused:UNUSED_PAD src0_sel:WORD_1
	v_add_f32_e32 v19, v19, v76
	v_cvt_f32_f16_e32 v80, v22
	v_add_f32_e32 v19, v19, v77
	v_cvt_f32_f16_sdwa v81, v22 dst_sel:DWORD dst_unused:UNUSED_PAD src0_sel:WORD_1
	v_add_f32_e32 v19, v19, v78
	v_cvt_f32_f16_e32 v82, v23
	v_add_f32_e32 v19, v19, v79
	v_cvt_f32_f16_sdwa v83, v23 dst_sel:DWORD dst_unused:UNUSED_PAD src0_sel:WORD_1
	v_add_f32_e32 v19, v19, v80
	v_cvt_f32_f16_e32 v84, v16
	v_add_f32_e32 v19, v19, v81
	v_cvt_f32_f16_sdwa v85, v16 dst_sel:DWORD dst_unused:UNUSED_PAD src0_sel:WORD_1
	v_add_f32_e32 v16, v19, v82
	v_cvt_f32_f16_e32 v86, v17
	v_add_f32_e32 v16, v16, v83
	v_cvt_f32_f16_sdwa v87, v17 dst_sel:DWORD dst_unused:UNUSED_PAD src0_sel:WORD_1
	v_add_f32_e32 v16, v16, v84
	v_cvt_f32_f16_e32 v88, v18
	v_add_f32_e32 v16, v16, v85
	v_cvt_f32_f16_sdwa v89, v18 dst_sel:DWORD dst_unused:UNUSED_PAD src0_sel:WORD_1
	v_add_f32_e32 v16, v16, v86
	v_add_f32_e32 v16, v16, v87
	v_add_f32_e32 v16, v16, v88
	v_add_f32_e32 v16, v16, v89
	v_add_f32_e32 v16, v16, v68
	v_add_f32_e32 v16, v16, v69
	ds_bpermute_b32 v17, v171, v16
	s_and_b64 s[6:7], exec, s[6:7]
	v_lshl_add_u64 v[38:39], v[38:39], 0, s[10:11]
	s_or_b64 s[14:15], s[6:7], s[14:15]
	s_waitcnt lgkmcnt(0)
	v_add_f32_e32 v16, v16, v17
	ds_bpermute_b32 v17, v172, v16
	s_waitcnt lgkmcnt(0)
	v_add_f32_e32 v16, v16, v17
	ds_bpermute_b32 v17, v173, v16
	s_waitcnt lgkmcnt(0)
	v_add_f32_e32 v16, v16, v17
	ds_bpermute_b32 v17, v174, v16
	s_waitcnt lgkmcnt(0)
	v_add_f32_e32 v16, v16, v17
	ds_bpermute_b32 v17, v175, v16
	s_waitcnt lgkmcnt(0)
	v_add_f32_e32 v57, v16, v17
	ds_bpermute_b32 v90, v176, v57
	global_load_dwordx4 v[16:19], v[46:47], off offset:16
	global_load_dwordx4 v[20:23], v[46:47], off
	global_load_dwordx4 v[24:27], v[40:41], off offset:16
	global_load_dwordx4 v[28:31], v[40:41], off
	global_load_dwordx4 v[204:207], v[48:49], off offset:16
	global_load_dwordx4 v[208:211], v[48:49], off
	global_load_dwordx4 v[212:215], v[42:43], off
	global_load_dwordx4 v[216:219], v[42:43], off offset:16
	global_load_dwordx4 v[220:223], v[50:51], off offset:16
	global_load_dwordx4 v[224:227], v[50:51], off
	global_load_dwordx4 v[228:231], v[44:45], off
	global_load_dwordx4 v[232:235], v[44:45], off offset:16
	global_load_dwordx4 v[240:243], v[52:53], off offset:16
	global_load_dwordx4 v[244:247], v[52:53], off
	global_load_dwordx4 v[248:251], v[54:55], off
	global_load_dwordx4 v[252:255], v[54:55], off offset:16
	s_waitcnt lgkmcnt(0)
	v_add_f32_e32 v57, v57, v90
	v_mul_f32_e32 v90, 0x3a000000, v57
	v_pk_add_f32 v[58:59], v[58:59], v[90:91] op_sel_hi:[1,0] neg_lo:[0,1] neg_hi:[0,1]
	v_pk_add_f32 v[60:61], v[60:61], v[90:91] op_sel_hi:[1,0] neg_lo:[0,1] neg_hi:[0,1]
	v_pk_mul_f32 v[92:93], v[58:59], v[58:59]
	v_pk_mul_f32 v[94:95], v[60:61], v[60:61]
	v_add_f32_e32 v57, v92, v93
	v_pk_add_f32 v[62:63], v[62:63], v[90:91] op_sel_hi:[1,0] neg_lo:[0,1] neg_hi:[0,1]
	v_add_f32_e32 v57, v94, v57
	v_pk_mul_f32 v[96:97], v[62:63], v[62:63]
	v_add_f32_e32 v57, v95, v57
	v_pk_add_f32 v[64:65], v[64:65], v[90:91] op_sel_hi:[1,0] neg_lo:[0,1] neg_hi:[0,1]
	v_add_f32_e32 v57, v96, v57
	v_pk_mul_f32 v[98:99], v[64:65], v[64:65]
	v_add_f32_e32 v57, v97, v57
	v_pk_add_f32 v[66:67], v[66:67], v[90:91] op_sel_hi:[1,0] neg_lo:[0,1] neg_hi:[0,1]
	v_add_f32_e32 v57, v98, v57
	v_pk_mul_f32 v[100:101], v[66:67], v[66:67]
	v_add_f32_e32 v57, v99, v57
	v_pk_add_f32 v[70:71], v[70:71], v[90:91] op_sel_hi:[1,0] neg_lo:[0,1] neg_hi:[0,1]
	v_add_f32_e32 v57, v100, v57
	v_pk_mul_f32 v[102:103], v[70:71], v[70:71]
	v_add_f32_e32 v57, v101, v57
	v_pk_add_f32 v[72:73], v[72:73], v[90:91] op_sel_hi:[1,0] neg_lo:[0,1] neg_hi:[0,1]
	v_add_f32_e32 v57, v102, v57
	v_pk_mul_f32 v[104:105], v[72:73], v[72:73]
	v_add_f32_e32 v57, v103, v57
	v_pk_add_f32 v[74:75], v[74:75], v[90:91] op_sel_hi:[1,0] neg_lo:[0,1] neg_hi:[0,1]
	v_add_f32_e32 v57, v104, v57
	v_pk_mul_f32 v[106:107], v[74:75], v[74:75]
	v_add_f32_e32 v57, v105, v57
; __device__ __forceinline__ void ln_phase(int wv, h16* X, const float* g, const float* b, float* out32, int G, const float* part, float alpha, float beta) {
;     ...
;         const float mean = wave_sum(s) * (1.f / DM); float s2 = 0.f;
; #pragma unroll
;         for (int e = 0; e < 32; ++e) { v[e] -= mean; s2 += v[e] * v[e]; }
;         const float rstd = 1.f / sqrtf(wave_sum(s2) * (1.f / DM) + LN_EPS);
; #pragma unroll
;         for (int j = 0; j < 4; ++j) { const int c0 = j * 512 + lane * 8;
;             const f32x4 g0 = *(const f32x4*)(g + c0), g1 = *(const f32x4*)(g + c0 + 4), b0 = *(const f32x4*)(b + c0), b1 = *(const f32x4*)(b + c0 + 4);
;             f32x4 o0, o1;
; #pragma unroll
;             for (int e = 0; e < 4; ++e) { o0[e] = v[j * 8 + e] * rstd * g0[e] + b0[e]; o1[e] = v[j * 8 + 4 + e] * rstd * g1[e] + b1[e]; }
;             if (out32) { *(f32x4*)(out32 + (size_t)row * DM + c0) = o0; *(f32x4*)(out32 + (size_t)row * DM + c0 + 4) = o1; }
;             else *(u32x4*)(xr + c0) = pg8::pack8(o0, o1); }
	v_pk_add_f32 v[76:77], v[76:77], v[90:91] op_sel_hi:[1,0] neg_lo:[0,1] neg_hi:[0,1]
	v_add_f32_e32 v57, v106, v57
	v_pk_mul_f32 v[108:109], v[76:77], v[76:77]
	v_add_f32_e32 v57, v107, v57
	v_pk_add_f32 v[78:79], v[78:79], v[90:91] op_sel_hi:[1,0] neg_lo:[0,1] neg_hi:[0,1]
	v_add_f32_e32 v57, v108, v57
	v_pk_mul_f32 v[110:111], v[78:79], v[78:79]
	v_add_f32_e32 v57, v109, v57
	v_pk_add_f32 v[80:81], v[80:81], v[90:91] op_sel_hi:[1,0] neg_lo:[0,1] neg_hi:[0,1]
	v_add_f32_e32 v57, v110, v57
	v_pk_mul_f32 v[112:113], v[80:81], v[80:81]
	v_add_f32_e32 v57, v111, v57
	v_pk_add_f32 v[82:83], v[82:83], v[90:91] op_sel_hi:[1,0] neg_lo:[0,1] neg_hi:[0,1]
	v_add_f32_e32 v57, v112, v57
	v_pk_mul_f32 v[114:115], v[82:83], v[82:83]
	v_add_f32_e32 v57, v113, v57
	v_pk_add_f32 v[84:85], v[84:85], v[90:91] op_sel_hi:[1,0] neg_lo:[0,1] neg_hi:[0,1]
	v_add_f32_e32 v57, v114, v57
	v_pk_mul_f32 v[116:117], v[84:85], v[84:85]
	v_add_f32_e32 v57, v115, v57
	v_pk_add_f32 v[86:87], v[86:87], v[90:91] op_sel_hi:[1,0] neg_lo:[0,1] neg_hi:[0,1]
	v_add_f32_e32 v57, v116, v57
	v_pk_mul_f32 v[118:119], v[86:87], v[86:87]
	v_add_f32_e32 v57, v117, v57
	v_pk_add_f32 v[88:89], v[88:89], v[90:91] op_sel_hi:[1,0] neg_lo:[0,1] neg_hi:[0,1]
	v_add_f32_e32 v57, v118, v57
	v_pk_mul_f32 v[120:121], v[88:89], v[88:89]
	v_add_f32_e32 v57, v119, v57
	v_pk_add_f32 v[90:91], v[68:69], v[90:91] op_sel_hi:[1,0] neg_lo:[0,1] neg_hi:[0,1]
	v_add_f32_e32 v57, v120, v57
	v_pk_mul_f32 v[68:69], v[90:91], v[90:91]
	v_add_f32_e32 v57, v121, v57
	v_add_f32_e32 v57, v68, v57
	v_add_f32_e32 v57, v69, v57
	ds_bpermute_b32 v68, v171, v57
	s_waitcnt lgkmcnt(0)
	v_add_f32_e32 v57, v57, v68
	ds_bpermute_b32 v68, v172, v57
	s_waitcnt lgkmcnt(0)
	v_add_f32_e32 v57, v57, v68
	ds_bpermute_b32 v68, v173, v57
	s_waitcnt lgkmcnt(0)
	v_add_f32_e32 v57, v57, v68
	ds_bpermute_b32 v68, v174, v57
	s_waitcnt lgkmcnt(0)
	v_add_f32_e32 v57, v57, v68
	ds_bpermute_b32 v68, v175, v57
	s_waitcnt lgkmcnt(0)
	v_add_f32_e32 v57, v57, v68
	ds_bpermute_b32 v68, v176, v57
	s_waitcnt lgkmcnt(0)
	v_add_f32_e32 v57, v57, v68
	v_fmamk_f32 v57, v57, 0x3a000000, v33
	v_mul_f32_e32 v68, 0x4f800000, v57
	v_cmp_gt_f32_e32 vcc, s4, v57
	s_nop 1
	v_cndmask_b32_e32 v57, v57, v68, vcc
	v_sqrt_f32_e32 v68, v57
	s_nop 0
	v_add_u32_e32 v69, -1, v68
	v_fma_f32 v92, -v69, v68, v57
	v_cmp_ge_f32_e64 s[8:9], 0, v92
	v_add_u32_e32 v92, 1, v68
	s_nop 0
	v_cndmask_b32_e64 v69, v68, v69, s[8:9]
	v_fma_f32 v68, -v92, v68, v57
	v_cmp_lt_f32_e64 s[8:9], 0, v68
	s_nop 1
	v_cndmask_b32_e64 v68, v69, v92, s[8:9]
	v_mul_f32_e32 v69, 0x37800000, v68
	v_cndmask_b32_e32 v68, v68, v69, vcc
	v_cmp_class_f32_e32 vcc, v57, v56
	s_nop 1
	v_cndmask_b32_e32 v57, v68, v57, vcc
	v_div_scale_f32 v92, s[8:9], v57, v57, 1.0
	v_rcp_f32_e32 v93, v92
	v_lshl_add_u64 v[68:69], v[36:37], 0, v[34:35]
	v_lshl_add_u64 v[36:37], v[36:37], 0, s[10:11]
	v_fma_f32 v94, -v92, v93, 1.0
	v_fmac_f32_e32 v93, v94, v93
	v_div_scale_f32 v94, vcc, 1.0, v57, 1.0
	v_mul_f32_e32 v95, v94, v93
	v_fma_f32 v96, -v92, v95, v94
	v_fmac_f32_e32 v95, v96, v93
	v_fma_f32 v92, -v92, v95, v94
	v_div_fmas_f32 v92, v92, v93, v95
	v_div_fixup_f32 v92, v92, v57, 1.0
	v_pk_mul_f32 v[58:59], v[58:59], v[92:93] op_sel_hi:[1,0]
	v_add_co_u32_e32 v94, vcc, s3, v68
	s_waitcnt vmcnt(0)
	v_pk_fma_f32 v[20:21], v[20:21], v[58:59], v[28:29]
	v_pk_mul_f32 v[28:29], v[62:63], v[92:93] op_sel_hi:[1,0]
	v_addc_co_u32_e32 v95, vcc, 0, v69, vcc
	v_pk_fma_f32 v[24:25], v[16:17], v[28:29], v[24:25]
	v_pk_mul_f32 v[16:17], v[60:61], v[92:93] op_sel_hi:[1,0]
	v_pk_mul_f32 v[58:59], v[66:67], v[92:93] op_sel_hi:[1,0]
	v_pk_fma_f32 v[22:23], v[22:23], v[16:17], v[30:31]
	v_pk_mul_f32 v[16:17], v[64:65], v[92:93] op_sel_hi:[1,0]
	v_pk_mul_f32 v[60:61], v[72:73], v[92:93] op_sel_hi:[1,0]
	v_pk_fma_f32 v[26:27], v[18:19], v[16:17], v[26:27]
	v_cvt_pk_f16_f32 v16, v20, v21
	v_cvt_pk_f16_f32 v17, v22, v23
	v_cvt_pk_f16_f32 v18, v24, v25
	v_cvt_pk_f16_f32 v19, v26, v27
	global_store_dwordx4 v[94:95], v[16:19], off
	s_nop 0
	v_pk_mul_f32 v[62:63], v[70:71], v[92:93] op_sel_hi:[1,0]
	v_pk_mul_f32 v[64:65], v[74:75], v[92:93] op_sel_hi:[1,0]
	v_pk_mul_f32 v[70:71], v[84:85], v[92:93] op_sel_hi:[1,0]
	v_pk_mul_f32 v[72:73], v[88:89], v[92:93] op_sel_hi:[1,0]
	v_pk_mul_f32 v[74:75], v[86:87], v[92:93] op_sel_hi:[1,0]
	v_pk_fma_f32 v[20:21], v[208:209], v[58:59], v[212:213]
	v_pk_fma_f32 v[24:25], v[204:205], v[60:61], v[216:217]
	v_pk_fma_f32 v[22:23], v[210:211], v[62:63], v[214:215]
	v_pk_fma_f32 v[26:27], v[206:207], v[64:65], v[218:219]
	v_cvt_pk_f16_f32 v16, v20, v21
	v_cvt_pk_f16_f32 v17, v22, v23
	v_cvt_pk_f16_f32 v18, v24, v25
	v_cvt_pk_f16_f32 v19, v26, v27
	global_store_dwordx4 v[94:95], v[16:19], off offset:1024
	s_nop 0
	v_pk_mul_f32 v[58:59], v[76:77], v[92:93] op_sel_hi:[1,0]
	v_pk_mul_f32 v[60:61], v[80:81], v[92:93] op_sel_hi:[1,0]
	v_pk_mul_f32 v[62:63], v[78:79], v[92:93] op_sel_hi:[1,0]
	v_pk_mul_f32 v[64:65], v[82:83], v[92:93] op_sel_hi:[1,0]
	v_pk_mul_f32 v[76:77], v[90:91], v[92:93] op_sel_hi:[1,0]
	v_pk_fma_f32 v[20:21], v[224:225], v[58:59], v[228:229]
	v_pk_fma_f32 v[24:25], v[220:221], v[60:61], v[232:233]
	v_pk_fma_f32 v[22:23], v[226:227], v[62:63], v[230:231]
	v_pk_fma_f32 v[26:27], v[222:223], v[64:65], v[234:235]
	v_cvt_pk_f16_f32 v16, v20, v21
	v_cvt_pk_f16_f32 v17, v22, v23
	v_cvt_pk_f16_f32 v18, v24, v25
	v_cvt_pk_f16_f32 v19, v26, v27
	global_store_dwordx4 v[94:95], v[16:19], off offset:2048
	s_nop 0
	v_mov_b64_e32 v[30:31], v[2:3]
	v_mov_b64_e32 v[26:27], v[6:7]
	v_mov_b64_e32 v[22:23], v[10:11]
	v_mov_b64_e32 v[28:29], v[0:1]
	v_mov_b64_e32 v[24:25], v[4:5]
	v_mov_b64_e32 v[20:21], v[8:9]
	v_pk_fma_f32 v[58:59], v[244:245], v[70:71], v[248:249]
	v_pk_fma_f32 v[62:63], v[240:241], v[72:73], v[252:253]
	v_pk_fma_f32 v[60:61], v[246:247], v[74:75], v[250:251]
	v_pk_fma_f32 v[64:65], v[242:243], v[76:77], v[254:255]
	v_cvt_pk_f16_f32 v16, v58, v59
	v_cvt_pk_f16_f32 v17, v60, v61
	v_cvt_pk_f16_f32 v18, v62, v63
	v_cvt_pk_f16_f32 v19, v64, v65
	global_store_dwordx4 v[94:95], v[16:19], off offset:3072
	s_nop 1
	v_mov_b64_e32 v[18:19], v[14:15]
	v_mov_b64_e32 v[16:17], v[12:13]
	s_andn2_b64 exec, exec, s[14:15]
	s_cbranch_execz .LBB0_2531
